# fused-norm row-statistics collect fetches the 4 partials with one 16-byte load (was 3 serialized round trips); first-barrier XCC census loads batched (was 16 serialized round trips)
# speedup vs baseline: 1.0097x; 1.0097x over previous
; __device__ __forceinline__ unsigned xb_ld(unsigned* p)              { return __hip_atomic_load(p, __ATOMIC_RELAXED, __HIP_MEMORY_SCOPE_AGENT); }
; __device__ __forceinline__ void xcd_barrier_complete(unsigned* bar, unsigned x, unsigned& nloc, unsigned& nx) {
;     ...
;     for (;;) {
;         sum = 0u; cnt = 0u; mine = 0u;
; #pragma unroll
;         for (unsigned j = 0; j < 16; ++j) { const unsigned c = xb_ld(&bar[XB_XCNT(j)]); sum += c; cnt += (c > 0u) ? 1u : 0u; mine = (j == x) ? c : mine; }
;         if (sum == G) break;
;         __builtin_amdgcn_s_sleep(1);
;         if ((++sp & 255u) == 0u) { if (xb_ld(&bar[XB_TMO])) break; if (sp > XB_SPIN_CAP) { atomicAdd(&bar[XB_TMO], 1u); break; } }
;     }
.LBB0_26:
	global_load_dword v0, v1, s[24:25] sc1
	global_load_dword v2, v1, s[24:25] offset:256 sc1
	global_load_dword v3, v1, s[24:25] offset:512 sc1
	global_load_dword v4, v1, s[24:25] offset:768 sc1
	global_load_dword v5, v1, s[24:25] offset:1024 sc1
	global_load_dword v6, v1, s[24:25] offset:1280 sc1
	global_load_dword v7, v1, s[24:25] offset:1536 sc1
	global_load_dword v8, v1, s[24:25] offset:1792 sc1
	global_load_dword v9, v1, s[24:25] offset:2048 sc1
	global_load_dword v10, v1, s[24:25] offset:2304 sc1
	global_load_dword v11, v1, s[24:25] offset:2560 sc1
	global_load_dword v12, v1, s[24:25] offset:2816 sc1
	global_load_dword v13, v1, s[24:25] offset:3072 sc1
	global_load_dword v14, v1, s[24:25] offset:3328 sc1
	global_load_dword v15, v1, s[24:25] offset:3584 sc1
	global_load_dword v16, v1, s[24:25] offset:3840 sc1
	s_mov_b64 s[4:5], -1
	s_mov_b64 s[2:3], -1
	s_waitcnt vmcnt(0)
	v_add_u32_e32 v17, v2, v0
	v_add_u32_e32 v17, v17, v3
	v_add_u32_e32 v17, v17, v4
	v_add_u32_e32 v17, v17, v5
	v_add_u32_e32 v17, v17, v6
	v_add_u32_e32 v17, v17, v7
	v_add_u32_e32 v17, v17, v8
	v_add_u32_e32 v17, v17, v9
	v_add_u32_e32 v17, v17, v10
	v_add_u32_e32 v17, v17, v11
	v_add_u32_e32 v17, v17, v12
	v_add_u32_e32 v17, v17, v13
	v_add_u32_e32 v17, v17, v14
	v_add_u32_e32 v17, v17, v15
	v_add_u32_e32 v17, v17, v16
	v_cmp_eq_u32_e32 vcc, s9, v17
	s_cbranch_vccnz .LBB0_25
	s_and_b32 s2, s10, 0xff
	s_cmp_eq_u32 s2, 0
	s_mov_b64 s[2:3], -1
	s_mov_b64 s[6:7], -1
	s_sleep 1
	s_cbranch_scc1 .LBB0_30
	s_and_b64 vcc, exec, s[6:7]
	s_cbranch_vccz .LBB0_25

; __device__ __forceinline__ void panel_ss_collect(const Unit& u, PG8_LAS unsigned char* lds, int wid, int lane, float* slots, unsigned* cnt, unsigned target) {
;     ...
;     asm volatile("s_waitcnt vmcnt(0) lgkmcnt(0)" ::: "memory"); __builtin_amdgcn_s_barrier(); asm volatile("" ::: "memory");
;     if (lane < 32) { const float* sl = slots + (size_t)(u.pm * BM + row) * 4; float t = 0.f;
; #pragma unroll
;         for (int q = 0; q < 4; ++q) t += __hip_atomic_load(sl + q, __ATOMIC_RELAXED, __HIP_MEMORY_SCOPE_AGENT);
;         S[row] = t; }
;     asm volatile("s_waitcnt lgkmcnt(0)" ::: "memory"); __builtin_amdgcn_s_barrier(); asm volatile("" ::: "memory");
.LBB0_178:
	s_waitcnt vmcnt(0) lgkmcnt(0)
	s_barrier
	s_lshl_b32 s29, s5, 5
	v_and_or_b32 v242, v236, 31, s29
	s_and_saveexec_b64 s[18:19], s[8:9]
	s_cbranch_execz .LBB0_180
	v_add_u32_e32 v142, s12, v242
	v_ashrrev_i32_e32 v143, 31, v142
	v_lshl_add_u64 v[142:143], v[142:143], 4, s[2:3]
	global_load_dwordx4 v[142:145], v[142:143], off sc1
	s_waitcnt vmcnt(0)
	v_add_f32_e32 v0, 0, v142
	v_add_f32_e32 v0, v0, v143
	v_add_f32_e32 v0, v0, v144
	v_add_f32_e32 v0, v0, v145
	v_lshl_add_u32 v142, v242, 2, 0
	ds_write_b32 v142, v0 offset:4096

; __device__ __forceinline__ void panel_ss_collect(const Unit& u, PG8_LAS unsigned char* lds, int wid, int lane, float* slots, unsigned* cnt, unsigned target) {
;     ...
;     asm volatile("s_waitcnt vmcnt(0) lgkmcnt(0)" ::: "memory"); __builtin_amdgcn_s_barrier(); asm volatile("" ::: "memory");
;     if (lane < 32) { const float* sl = slots + (size_t)(u.pm * BM + row) * 4; float t = 0.f;
; #pragma unroll
;         for (int q = 0; q < 4; ++q) t += __hip_atomic_load(sl + q, __ATOMIC_RELAXED, __HIP_MEMORY_SCOPE_AGENT);
;         S[row] = t; }
;     asm volatile("s_waitcnt lgkmcnt(0)" ::: "memory"); __builtin_amdgcn_s_barrier(); asm volatile("" ::: "memory");
.LBB0_222:
	s_waitcnt vmcnt(0) lgkmcnt(0)
	s_barrier
	s_and_saveexec_b64 s[0:1], s[8:9]
	s_cbranch_execz .LBB0_224
	v_add_u32_e32 v146, s12, v242
	v_ashrrev_i32_e32 v147, 31, v146
	v_lshl_add_u64 v[146:147], v[146:147], 4, s[2:3]
	global_load_dwordx4 v[146:149], v[146:147], off sc1
	s_waitcnt vmcnt(0)
	v_add_f32_e32 v0, 0, v146
	v_add_f32_e32 v0, v0, v147
	v_add_f32_e32 v0, v0, v148
	v_add_f32_e32 v0, v0, v149
	v_lshl_add_u32 v146, v242, 2, 0
	ds_write_b32 v146, v0 offset:4096
